# grid barrier: non-leader workgroups poll the global generation word directly instead of waiting for their XCD leader's relay (one hop less per barrier)
# speedup vs baseline: 1.0271x; 1.0271x over previous
.LBB0_390:
	s_or_b64 exec, exec, s[12:13]
	v_cvt_f32_u32_e32 v5, v3
	s_waitcnt vmcnt(0)
	v_readfirstlane_b32 s2, v4
	v_sub_u32_e32 v4, 0, v3
	v_rcp_iflag_f32_e32 v5, v5
	v_add_u32_e32 v6, s2, v1
	v_mul_f32_e32 v5, 0x4f7ffffe, v5
	v_cvt_u32_f32_e32 v5, v5
	v_mul_lo_u32 v1, v4, v5
	v_mul_hi_u32 v1, v5, v1
	v_add_u32_e32 v1, v5, v1
	v_mul_hi_u32 v1, v6, v1
	v_mul_lo_u32 v4, v1, v3
	v_sub_u32_e32 v4, v6, v4
	v_add_u32_e32 v5, 1, v1
	v_cmp_ge_u32_e32 vcc, v4, v3
	s_nop 1
	v_cndmask_b32_e32 v1, v1, v5, vcc
	v_sub_u32_e32 v5, v4, v3
	v_cndmask_b32_e32 v4, v4, v5, vcc
	v_add_u32_e32 v5, 1, v1
	v_cmp_ge_u32_e32 vcc, v4, v3
	v_add_u32_e32 v4, 1, v6
	s_nop 0
	v_cndmask_b32_e32 v1, v1, v5, vcc
	v_mul_lo_u32 v5, v3, v1
	v_add_u32_e32 v3, v5, v3
	v_cmp_ne_u32_e32 vcc, v4, v3
	s_and_saveexec_b64 s[2:3], vcc
	s_xor_b64 s[12:13], exec, s[2:3]
	s_cbranch_execz .LBB0_404
	v_readlane_b32 s2, v254, 47
	v_readlane_b32 s3, v254, 48
	s_waitcnt lgkmcnt(0)
	s_nop 3
	global_load_dword v2, v0, s[2:3] sc1
	s_waitcnt vmcnt(0)
	v_cmp_eq_u32_e32 vcc, v2, v1
	s_and_saveexec_b64 s[14:15], vcc
	s_cbranch_execz .LBB0_403
	s_mov_b32 s2, 1
	s_mov_b64 s[20:21], 0
	s_branch .LBB0_394
